# H + attention QK section with three d-steps of K fragments in flight (sets in v[120:135]) + early first-tile K reads
# speedup vs baseline: 1.0029x; 1.0029x over previous
.LBB0_3761:
	s_add_i32 s0, s51, 2
	s_sub_i32 s1, s0, s48
	s_min_u32 s2, s0, s1
	s_lshl_b64 s[0:1], s[2:3], 13
	v_lshl_add_u64 v[14:15], v[180:181], 0, s[0:1]
	v_lshl_add_u64 v[218:219], v[182:183], 0, s[0:1]
	s_mov_b32 m0, s70
	s_nop 0
	global_load_lds_dwordx4 v[14:15], off
	s_add_i32 m0, s70, 0x2000
	s_nop 0
	global_load_lds_dwordx4 v[218:219], off
	s_add_i32 s0, s51, 3
	s_sub_i32 s1, s0, s48
	s_min_u32 s2, s0, s1
	s_lshl_b64 s[0:1], s[2:3], 13
	v_lshl_add_u64 v[14:15], v[180:181], 0, s[0:1]
	v_lshl_add_u64 v[218:219], v[182:183], 0, s[0:1]
	s_add_i32 m0, s70, 0x4000
	s_nop 0
	global_load_lds_dwordx4 v[14:15], off
	s_add_i32 m0, s70, 0x6000
	s_nop 0
	global_load_lds_dwordx4 v[218:219], off
	s_cmp_gt_u32 s51, s47
	s_cbranch_scc1 .LBB0_3765
	ds_read_b128 v[120:123], v200 offset:2048
	ds_read_b128 v[124:127], v200 offset:2560
	ds_read_b128 v[128:131], v200 offset:4096
	ds_read_b128 v[132:135], v200 offset:4608
	v_lshrrev_b32_e32 v1, v160, v152
	v_lshrrev_b32_e32 v14, v160, v153
	v_bitop3_b32 v228, v1, s27, v1 bitop3:0xc
	v_bitop3_b32 v229, v1, s28, v1 bitop3:0xc
	v_bitop3_b32 v230, v1, s29, v1 bitop3:0xc
	v_bitop3_b32 v231, v1, s30, v1 bitop3:0xc
	s_waitcnt lgkmcnt(5)
	v_mfma_f32_32x32x16_bf16 v[80:95], v[6:9], v[144:147], v[64:79]
	v_mul_u32_u24_e32 v228, 0xf000, v228
	v_mul_u32_u24_e32 v229, 0x7800, v229
	v_mul_u32_u24_e32 v230, 0x3c00, v230
	v_mul_u32_u24_e32 v231, 0x1e00, v231
	s_waitcnt lgkmcnt(4)
	v_mfma_f32_32x32x16_bf16 v[96:111], v[10:13], v[144:147], v[64:79]
	ds_read_b128 v[6:9], v200 offset:6144
	ds_read_b128 v[10:13], v200 offset:6656
	v_bitop3_b32 v232, v14, s27, v14 bitop3:0xc
	v_bitop3_b32 v233, v14, s28, v14 bitop3:0xc
	v_bitop3_b32 v234, v14, s29, v14 bitop3:0xc
	v_bitop3_b32 v235, v14, s30, v14 bitop3:0xc
	v_mul_u32_u24_e32 v232, 0xf000, v232
	v_mul_u32_u24_e32 v233, 0x7800, v233
	v_mul_u32_u24_e32 v234, 0x3c00, v234
	v_mul_u32_u24_e32 v235, 0x1e00, v235
	s_waitcnt lgkmcnt(5)
	v_mfma_f32_32x32x16_bf16 v[80:95], v[120:123], v[136:139], v[80:95]
	v_bitop3_b32 v236, v1, s31, v1 bitop3:0xc
	v_bitop3_b32 v237, v1, s33, v1 bitop3:0xc
	v_bitop3_b32 v238, v1, s34, v1 bitop3:0xc
	v_bitop3_b32 v239, v1, s35, v1 bitop3:0xc
	s_waitcnt lgkmcnt(4)
	v_mfma_f32_32x32x16_bf16 v[96:111], v[124:127], v[136:139], v[96:111]
	v_mul_u32_u24_e32 v236, 0xf00, v236
	v_mul_u32_u24_e32 v237, 0x780, v237
	v_mul_u32_u24_e32 v238, 0x3c0, v238
	v_mul_u32_u24_e32 v239, 0x1e0, v239
	v_bitop3_b32 v224, v14, s31, v14 bitop3:0xc
	v_bitop3_b32 v225, v14, s33, v14 bitop3:0xc
	v_bitop3_b32 v226, v14, s34, v14 bitop3:0xc
	v_bitop3_b32 v227, v14, s35, v14 bitop3:0xc
	s_waitcnt lgkmcnt(3)
	v_mfma_f32_32x32x16_bf16 v[80:95], v[128:131], v[140:143], v[80:95]
	v_mul_u32_u24_e32 v224, 0xf00, v224
	v_mul_u32_u24_e32 v225, 0x780, v225
	v_mul_u32_u24_e32 v226, 0x3c0, v226
	v_mul_u32_u24_e32 v227, 0x1e0, v227
	s_waitcnt lgkmcnt(2)
	v_mfma_f32_32x32x16_bf16 v[96:111], v[132:135], v[140:143], v[96:111]
	s_xor_b64 s[4:5], s[20:21], -1
	s_waitcnt lgkmcnt(1)
	v_mfma_f32_32x32x16_bf16 v[80:95], v[6:9], v[148:151], v[80:95]
	s_waitcnt lgkmcnt(0)
	v_mfma_f32_32x32x16_bf16 v[96:111], v[10:13], v[148:151], v[96:111]
	v_mfma_f32_32x32x16_bf16 v[80:95], v[112:115], v[228:231], v[80:95]
	v_mfma_f32_32x32x16_bf16 v[96:111], v[112:115], v[232:235], v[96:111]
	v_mfma_f32_32x32x16_bf16 v[80:95], v[116:119], v[236:239], v[80:95]
	v_mfma_f32_32x32x16_bf16 v[96:111], v[116:119], v[224:227], v[96:111]
	s_nop 15
	s_nop 7
	v_max3_f32 v1, v80, v81, v82
	v_max3_f32 v6, v83, v84, v85
	v_max3_f32 v1, v1, v86, v87
	v_max3_f32 v6, v6, v88, v89
	v_max3_f32 v1, v1, v90, v91
	v_max3_f32 v6, v6, v92, v93
	v_max3_f32 v1, v1, v94, v95
	v_max_f32 v1, v1, v6
	s_nop 0
	v_max3_f32 v7, v96, v97, v98
	v_max3_f32 v6, v99, v100, v101
	v_max3_f32 v7, v7, v102, v103
	v_max3_f32 v6, v6, v104, v105
	v_max3_f32 v7, v7, v106, v107
	v_max3_f32 v6, v6, v108, v109
	v_max3_f32 v7, v7, v110, v111
	v_max3_f32 v7, v7, v6, v1
	s_nop 0
	v_mov_b32_e32 v1, v7
	s_nop 1
	v_permlane32_swap_b32_e32 v7, v1
	v_max_f32_e32 v1, v1, v1
	v_max_f32_e32 v6, v7, v7
	v_max_f32_e32 v1, v6, v1
	v_cmp_lt_f32_e64 s[0:1], s36, v1
	s_and_b64 s[10:11], s[0:1], s[4:5]
	v_cmp_lt_f32_e32 vcc, s37, v1
	s_or_b64 s[4:5], vcc, s[10:11]
	v_cndmask_b32_e64 v6, 0, 1, s[4:5]
	v_cmp_ne_u32_e32 vcc, 0, v6
	s_cbranch_vccz .LBB0_3764
	v_cndmask_b32_e64 v6, 0, v1, s[4:5]
	v_exp_f32_e64 v1, -v6
	v_add_f32_e32 v171, v171, v6
	s_or_b64 s[0:1], s[20:21], s[0:1]
	v_xor_b32_e32 v64, 0x80000000, v171
	v_cndmask_b32_e64 v8, v1, 1.0, s[10:11]
	s_andn2_b64 s[4:5], s[20:21], exec
	s_and_b64 s[0:1], s[0:1], exec
	v_pk_add_f32 v[80:81], v[80:81], v[6:7] op_sel_hi:[1,0] neg_lo:[0,1] neg_hi:[0,1]
	v_pk_add_f32 v[96:97], v[96:97], v[6:7] op_sel_hi:[1,0] neg_lo:[0,1] neg_hi:[0,1]
	v_pk_add_f32 v[82:83], v[82:83], v[6:7] op_sel_hi:[1,0] neg_lo:[0,1] neg_hi:[0,1]
	v_pk_add_f32 v[98:99], v[98:99], v[6:7] op_sel_hi:[1,0] neg_lo:[0,1] neg_hi:[0,1]
	v_pk_add_f32 v[84:85], v[84:85], v[6:7] op_sel_hi:[1,0] neg_lo:[0,1] neg_hi:[0,1]
	v_pk_add_f32 v[100:101], v[100:101], v[6:7] op_sel_hi:[1,0] neg_lo:[0,1] neg_hi:[0,1]
	v_pk_add_f32 v[86:87], v[86:87], v[6:7] op_sel_hi:[1,0] neg_lo:[0,1] neg_hi:[0,1]
	v_pk_add_f32 v[102:103], v[102:103], v[6:7] op_sel_hi:[1,0] neg_lo:[0,1] neg_hi:[0,1]
	v_pk_add_f32 v[88:89], v[88:89], v[6:7] op_sel_hi:[1,0] neg_lo:[0,1] neg_hi:[0,1]
	v_pk_add_f32 v[104:105], v[104:105], v[6:7] op_sel_hi:[1,0] neg_lo:[0,1] neg_hi:[0,1]
	v_pk_add_f32 v[90:91], v[90:91], v[6:7] op_sel_hi:[1,0] neg_lo:[0,1] neg_hi:[0,1]
	v_pk_add_f32 v[106:107], v[106:107], v[6:7] op_sel_hi:[1,0] neg_lo:[0,1] neg_hi:[0,1]
	v_pk_add_f32 v[92:93], v[92:93], v[6:7] op_sel_hi:[1,0] neg_lo:[0,1] neg_hi:[0,1]
	v_pk_add_f32 v[108:109], v[108:109], v[6:7] op_sel_hi:[1,0] neg_lo:[0,1] neg_hi:[0,1]
	v_pk_add_f32 v[94:95], v[94:95], v[6:7] op_sel_hi:[1,0] neg_lo:[0,1] neg_hi:[0,1]
	v_pk_add_f32 v[110:111], v[110:111], v[6:7] op_sel_hi:[1,0] neg_lo:[0,1] neg_hi:[0,1]
	v_mov_b32_e32 v65, v64
	v_mov_b32_e32 v66, v64
	v_mov_b32_e32 v67, v64
	v_mov_b32_e32 v68, v64
	v_mov_b32_e32 v69, v64
	v_mov_b32_e32 v70, v64
	v_mov_b32_e32 v71, v64
	v_mov_b32_e32 v72, v64
	v_mov_b32_e32 v73, v64
	v_mov_b32_e32 v74, v64
	v_mov_b32_e32 v75, v64
	v_mov_b32_e32 v76, v64
	v_mov_b32_e32 v77, v64
	v_mov_b32_e32 v78, v64
	v_mov_b32_e32 v79, v64
	v_pk_mul_f32 v[30:31], v[30:31], v[8:9] op_sel_hi:[1,0]
	v_pk_mul_f32 v[28:29], v[28:29], v[8:9] op_sel_hi:[1,0]
	v_pk_mul_f32 v[26:27], v[26:27], v[8:9] op_sel_hi:[1,0]
	v_pk_mul_f32 v[24:25], v[24:25], v[8:9] op_sel_hi:[1,0]
	v_pk_mul_f32 v[22:23], v[22:23], v[8:9] op_sel_hi:[1,0]
	v_pk_mul_f32 v[20:21], v[20:21], v[8:9] op_sel_hi:[1,0]
	v_pk_mul_f32 v[18:19], v[18:19], v[8:9] op_sel_hi:[1,0]
	v_pk_mul_f32 v[16:17], v[16:17], v[8:9] op_sel_hi:[1,0]
	v_pk_mul_f32 v[46:47], v[46:47], v[8:9] op_sel_hi:[1,0]
	v_pk_mul_f32 v[44:45], v[44:45], v[8:9] op_sel_hi:[1,0]
	v_pk_mul_f32 v[42:43], v[42:43], v[8:9] op_sel_hi:[1,0]
	v_pk_mul_f32 v[40:41], v[40:41], v[8:9] op_sel_hi:[1,0]
	v_pk_mul_f32 v[38:39], v[38:39], v[8:9] op_sel_hi:[1,0]
	v_pk_mul_f32 v[36:37], v[36:37], v[8:9] op_sel_hi:[1,0]
	v_pk_mul_f32 v[34:35], v[34:35], v[8:9] op_sel_hi:[1,0]
	v_pk_mul_f32 v[32:33], v[32:33], v[8:9] op_sel_hi:[1,0]
	v_pk_mul_f32 v[62:63], v[62:63], v[8:9] op_sel_hi:[1,0]
	v_pk_mul_f32 v[60:61], v[60:61], v[8:9] op_sel_hi:[1,0]
	v_pk_mul_f32 v[58:59], v[58:59], v[8:9] op_sel_hi:[1,0]
	v_pk_mul_f32 v[56:57], v[56:57], v[8:9] op_sel_hi:[1,0]
	v_pk_mul_f32 v[54:55], v[54:55], v[8:9] op_sel_hi:[1,0]
	v_pk_mul_f32 v[52:53], v[52:53], v[8:9] op_sel_hi:[1,0]
	v_pk_mul_f32 v[50:51], v[50:51], v[8:9] op_sel_hi:[1,0]
	v_pk_mul_f32 v[48:49], v[48:49], v[8:9] op_sel_hi:[1,0]
	s_or_b64 s[20:21], s[4:5], s[0:1]

; __device__ __forceinline__ float max32raw(const f32x16& a, const f32x16& b) {
;     float x, y;
;     asm volatile("s_nop 15\n\ts_nop 7\n\t"
;         "v_max3_f32 %0, %2, %3, %4\n\tv_max3_f32 %1, %5, %6, %7\n\t"
;         "v_max3_f32 %0, %0, %8, %9\n\tv_max3_f32 %1, %1, %10, %11\n\t"
;         "v_max3_f32 %0, %0, %12, %13\n\tv_max3_f32 %1, %1, %14, %15\n\t"
;         "v_max3_f32 %0, %0, %16, %17\n\tv_max_f32 %0, %0, %1"
;         : "=&v"(x), "=&v"(y)
;         : "v"(a[0]), "v"(a[1]), "v"(a[2]), "v"(a[3]), "v"(a[4]), "v"(a[5]), "v"(a[6]), "v"(a[7]), "v"(a[8]), "v"(a[9]), "v"(a[10]), "v"(a[11]), "v"(a[12]), "v"(a[13]), "v"(a[14]), "v"(a[15]));
;     float u, v;
;     asm volatile("v_max3_f32 %0, %2, %3, %4\n\tv_max3_f32 %1, %5, %6, %7\n\t"
;         "v_max3_f32 %0, %0, %8, %9\n\tv_max3_f32 %1, %1, %10, %11\n\t"
;         "v_max3_f32 %0, %0, %12, %13\n\tv_max3_f32 %1, %1, %14, %15\n\t"
;         "v_max3_f32 %0, %0, %16, %17\n\tv_max3_f32 %0, %0, %1, %18"
;         : "=&v"(u), "=&v"(v)
;         : "v"(b[0]), "v"(b[1]), "v"(b[2]), "v"(b[3]), "v"(b[4]), "v"(b[5]), "v"(b[6]), "v"(b[7]), "v"(b[8]), "v"(b[9]), "v"(b[10]), "v"(b[11]), "v"(b[12]), "v"(b[13]), "v"(b[14]), "v"(b[15]), "v"(x));
;     return u;
; }
.LBB0_3765:
	s_cmp_ge_u32 s51, s47
	s_cbranch_scc1 .LBB0_3770
	ds_read_b128 v[6:9], v200 offset:16384
	ds_read_b128 v[10:13], v200 offset:16896
	ds_read_b128 v[120:123], v200 offset:18432
	ds_read_b128 v[124:127], v200 offset:18944
	ds_read_b128 v[128:131], v200 offset:20480
	ds_read_b128 v[132:135], v200 offset:20992
	v_lshrrev_b32_e32 v1, v160, v154
	v_lshrrev_b32_e32 v14, v160, v155
	v_bitop3_b32 v228, v1, s27, v1 bitop3:0xc
	v_bitop3_b32 v229, v1, s28, v1 bitop3:0xc
	v_bitop3_b32 v230, v1, s29, v1 bitop3:0xc
	v_bitop3_b32 v231, v1, s30, v1 bitop3:0xc
	s_waitcnt lgkmcnt(5)
	v_mfma_f32_32x32x16_bf16 v[80:95], v[6:9], v[144:147], v[64:79]
	v_mul_u32_u24_e32 v228, 0xf000, v228
	v_mul_u32_u24_e32 v229, 0x7800, v229
	v_mul_u32_u24_e32 v230, 0x3c00, v230
	v_mul_u32_u24_e32 v231, 0x1e00, v231
	s_waitcnt lgkmcnt(4)
	v_mfma_f32_32x32x16_bf16 v[96:111], v[10:13], v[144:147], v[64:79]
	ds_read_b128 v[6:9], v200 offset:22528
	ds_read_b128 v[10:13], v200 offset:23040
	v_bitop3_b32 v232, v14, s27, v14 bitop3:0xc
	v_bitop3_b32 v233, v14, s28, v14 bitop3:0xc
	v_bitop3_b32 v234, v14, s29, v14 bitop3:0xc
	v_bitop3_b32 v235, v14, s30, v14 bitop3:0xc
	v_mul_u32_u24_e32 v232, 0xf000, v232
	v_mul_u32_u24_e32 v233, 0x7800, v233
	v_mul_u32_u24_e32 v234, 0x3c00, v234
	v_mul_u32_u24_e32 v235, 0x1e00, v235
	s_waitcnt lgkmcnt(5)
	v_mfma_f32_32x32x16_bf16 v[80:95], v[120:123], v[136:139], v[80:95]
	v_bitop3_b32 v236, v1, s31, v1 bitop3:0xc
	v_bitop3_b32 v237, v1, s33, v1 bitop3:0xc
	v_bitop3_b32 v238, v1, s34, v1 bitop3:0xc
	v_bitop3_b32 v239, v1, s35, v1 bitop3:0xc
	s_waitcnt lgkmcnt(4)
	v_mfma_f32_32x32x16_bf16 v[96:111], v[124:127], v[136:139], v[96:111]
	v_mul_u32_u24_e32 v236, 0xf00, v236
	v_mul_u32_u24_e32 v237, 0x780, v237
	v_mul_u32_u24_e32 v238, 0x3c0, v238
	v_mul_u32_u24_e32 v239, 0x1e0, v239
	v_bitop3_b32 v224, v14, s31, v14 bitop3:0xc
	v_bitop3_b32 v225, v14, s33, v14 bitop3:0xc
	v_bitop3_b32 v226, v14, s34, v14 bitop3:0xc
	v_bitop3_b32 v227, v14, s35, v14 bitop3:0xc
	s_waitcnt lgkmcnt(3)
	v_mfma_f32_32x32x16_bf16 v[80:95], v[128:131], v[140:143], v[80:95]
	v_mul_u32_u24_e32 v224, 0xf00, v224
	v_mul_u32_u24_e32 v225, 0x780, v225
	v_mul_u32_u24_e32 v226, 0x3c0, v226
	v_mul_u32_u24_e32 v227, 0x1e0, v227
	s_waitcnt lgkmcnt(2)
	v_mfma_f32_32x32x16_bf16 v[96:111], v[132:135], v[140:143], v[96:111]
	s_xor_b64 s[4:5], s[20:21], -1
	v_cndmask_b32_e64 v1, 0, 1, s[4:5]
	v_cmp_ne_u32_e32 vcc, 0, v1
	s_waitcnt lgkmcnt(1)
	v_mfma_f32_32x32x16_bf16 v[80:95], v[6:9], v[148:151], v[80:95]
	s_waitcnt lgkmcnt(0)
	v_mfma_f32_32x32x16_bf16 v[96:111], v[10:13], v[148:151], v[96:111]
	v_mfma_f32_32x32x16_bf16 v[80:95], v[112:115], v[228:231], v[80:95]
	v_mfma_f32_32x32x16_bf16 v[96:111], v[112:115], v[232:235], v[96:111]
	v_mfma_f32_32x32x16_bf16 v[80:95], v[116:119], v[236:239], v[80:95]
	v_mfma_f32_32x32x16_bf16 v[96:111], v[116:119], v[224:227], v[96:111]
	s_cbranch_vccz .LBB0_3769
	s_nop 15
	s_nop 7
	v_max3_f32 v1, v80, v81, v82
	v_max3_f32 v6, v83, v84, v85
	v_max3_f32 v1, v1, v86, v87
	v_max3_f32 v6, v6, v88, v89
	v_max3_f32 v1, v1, v90, v91
	v_max3_f32 v6, v6, v92, v93
	v_max3_f32 v1, v1, v94, v95
	v_max_f32 v1, v1, v6
	s_nop 0
	v_max3_f32 v7, v96, v97, v98
	v_max3_f32 v6, v99, v100, v101
	v_max3_f32 v7, v7, v102, v103
	v_max3_f32 v6, v6, v104, v105
	v_max3_f32 v7, v7, v106, v107
	v_max3_f32 v6, v6, v108, v109
	v_max3_f32 v7, v7, v110, v111
	v_max3_f32 v7, v7, v6, v1
	s_nop 0
	v_mov_b32_e32 v1, v7
	s_nop 1
	v_permlane32_swap_b32_e32 v7, v1
	v_max_f32_e32 v1, v1, v1
	v_max_f32_e32 v6, v7, v7
	v_max_f32_e32 v1, v6, v1
	v_cmp_lt_f32_e64 s[0:1], s36, v1
	s_and_b64 s[10:11], s[0:1], s[4:5]
	v_cmp_lt_f32_e32 vcc, s37, v1
	s_or_b64 s[4:5], vcc, s[10:11]
	v_cndmask_b32_e64 v6, 0, 1, s[4:5]
	v_cmp_ne_u32_e32 vcc, 0, v6
	s_cbranch_vccz .LBB0_3769
	v_cndmask_b32_e64 v1, 0, v1, s[4:5]
	v_exp_f32_e64 v6, -v1
	v_add_f32_e32 v171, v171, v1
	s_or_b64 s[0:1], s[20:21], s[0:1]
	v_xor_b32_e32 v64, 0x80000000, v171
	v_cndmask_b32_e64 v6, v6, 1.0, s[10:11]
	s_andn2_b64 s[4:5], s[20:21], exec
	s_and_b64 s[0:1], s[0:1], exec
	v_mov_b32_e32 v65, v64
	v_mov_b32_e32 v66, v64
	v_mov_b32_e32 v67, v64
	v_mov_b32_e32 v68, v64
	v_mov_b32_e32 v69, v64
	v_mov_b32_e32 v70, v64
	v_mov_b32_e32 v71, v64
	v_mov_b32_e32 v72, v64
	v_mov_b32_e32 v73, v64
	v_mov_b32_e32 v74, v64
	v_mov_b32_e32 v75, v64
	v_mov_b32_e32 v76, v64
	v_mov_b32_e32 v77, v64
	v_mov_b32_e32 v78, v64
	v_mov_b32_e32 v79, v64
	v_pk_mul_f32 v[30:31], v[30:31], v[6:7] op_sel_hi:[1,0]
	v_pk_mul_f32 v[28:29], v[28:29], v[6:7] op_sel_hi:[1,0]
	v_pk_mul_f32 v[26:27], v[26:27], v[6:7] op_sel_hi:[1,0]
	v_pk_mul_f32 v[24:25], v[24:25], v[6:7] op_sel_hi:[1,0]
	v_pk_mul_f32 v[22:23], v[22:23], v[6:7] op_sel_hi:[1,0]
	v_pk_mul_f32 v[20:21], v[20:21], v[6:7] op_sel_hi:[1,0]
	v_pk_mul_f32 v[18:19], v[18:19], v[6:7] op_sel_hi:[1,0]
	v_pk_mul_f32 v[16:17], v[16:17], v[6:7] op_sel_hi:[1,0]
	v_pk_mul_f32 v[46:47], v[46:47], v[6:7] op_sel_hi:[1,0]
	v_pk_mul_f32 v[44:45], v[44:45], v[6:7] op_sel_hi:[1,0]
	v_pk_mul_f32 v[42:43], v[42:43], v[6:7] op_sel_hi:[1,0]
	v_pk_mul_f32 v[40:41], v[40:41], v[6:7] op_sel_hi:[1,0]
	v_pk_mul_f32 v[38:39], v[38:39], v[6:7] op_sel_hi:[1,0]
	v_pk_mul_f32 v[36:37], v[36:37], v[6:7] op_sel_hi:[1,0]
	v_pk_mul_f32 v[34:35], v[34:35], v[6:7] op_sel_hi:[1,0]
	v_pk_mul_f32 v[32:33], v[32:33], v[6:7] op_sel_hi:[1,0]
	v_pk_mul_f32 v[62:63], v[62:63], v[6:7] op_sel_hi:[1,0]
	v_pk_mul_f32 v[60:61], v[60:61], v[6:7] op_sel_hi:[1,0]
	v_pk_mul_f32 v[58:59], v[58:59], v[6:7] op_sel_hi:[1,0]
	v_pk_mul_f32 v[56:57], v[56:57], v[6:7] op_sel_hi:[1,0]
	v_pk_mul_f32 v[54:55], v[54:55], v[6:7] op_sel_hi:[1,0]
	v_pk_mul_f32 v[52:53], v[52:53], v[6:7] op_sel_hi:[1,0]
	v_pk_mul_f32 v[50:51], v[50:51], v[6:7] op_sel_hi:[1,0]
	v_pk_mul_f32 v[48:49], v[48:49], v[6:7] op_sel_hi:[1,0]
	v_sub_f32_e32 v95, v95, v1
	v_sub_f32_e32 v94, v94, v1
	v_sub_f32_e32 v93, v93, v1
	v_sub_f32_e32 v92, v92, v1
	v_sub_f32_e32 v91, v91, v1
	v_sub_f32_e32 v90, v90, v1
	v_sub_f32_e32 v89, v89, v1
	v_sub_f32_e32 v88, v88, v1
	v_sub_f32_e32 v87, v87, v1
	v_sub_f32_e32 v86, v86, v1
	v_sub_f32_e32 v85, v85, v1
	v_sub_f32_e32 v84, v84, v1
	v_sub_f32_e32 v83, v83, v1
	v_sub_f32_e32 v82, v82, v1
	v_sub_f32_e32 v81, v81, v1
	v_sub_f32_e32 v80, v80, v1
	v_sub_f32_e32 v111, v111, v1
	v_sub_f32_e32 v110, v110, v1
	v_sub_f32_e32 v109, v109, v1
	v_sub_f32_e32 v108, v108, v1
	v_sub_f32_e32 v107, v107, v1
	v_sub_f32_e32 v106, v106, v1
	v_sub_f32_e32 v105, v105, v1
	v_sub_f32_e32 v104, v104, v1
	v_sub_f32_e32 v103, v103, v1
	v_sub_f32_e32 v102, v102, v1
	v_sub_f32_e32 v101, v101, v1
	v_sub_f32_e32 v100, v100, v1
	v_sub_f32_e32 v99, v99, v1
	v_sub_f32_e32 v98, v98, v1
	v_sub_f32_e32 v97, v97, v1
	v_sub_f32_e32 v96, v96, v1
	s_or_b64 s[20:21], s[4:5], s[0:1]
